# v52 + attention slow-path K/V LDS-DMA in saddr form for full tiles (no 64-bit VALU address math, no row clamps)
# baseline (speedup 1.0000x reference)
.LBB0_1306:
	s_add_i32 s6, s95, 2
	s_cmp_le_u32 s6, s70
	s_cselect_b64 s[74:75], -1, 0
	s_cmp_gt_u32 s6, s70
	s_cbranch_scc1 .LBB0_1310
	s_cmp_lg_u32 s91, 0
	s_cbranch_scc1 .Lslow_dma_clamped
	s_cmp_lt_u32 s90, 64
	s_cbranch_scc1 .Lslow_dma_clamped
	s_add_u32 s98, s0, s72
	s_addc_u32 s99, s1, s73
	s_lshl_b32 s6, s88, 14
	s_add_i32 s7, s87, s6
	s_mov_b32 m0, s7
	s_add_i32 s6, s95, 2
	s_and_b32 s6, s6, 3
	global_load_lds_dwordx4 v239, s[98:99]
	s_addk_i32 s7, 0x400
	s_mov_b32 m0, s7
	s_lshl_b32 s6, s6, 14
	s_add_i32 s6, s85, s6
	global_load_lds_dwordx4 v240, s[98:99]
	s_add_u32 s98, s66, s72
	s_addc_u32 s99, s67, s73
	s_mov_b32 m0, s6
	s_addk_i32 s6, 0x400
	s_nop 0
	global_load_lds_dwordx4 v241, s[98:99]
	s_mov_b32 m0, s6
	s_nop 0
	global_load_lds_dwordx4 v242, s[98:99]
	s_branch .Lslow_dma_done
.Lslow_dma_clamped:
	v_cmp_lt_i64_e64 s[6:7], s[90:91], 64
	s_and_b64 s[6:7], s[6:7], exec
	s_cselect_b32 s6, s90, 64
	s_cselect_b32 s7, s91, 0
	s_add_u32 s6, s6, -1
	s_addc_u32 s7, s7, -1
	v_mov_b32_e32 v153, s7
	v_cmp_lt_i64_e32 vcc, s[6:7], v[2:3]
	v_mov_b32_e32 v155, s6
	s_nop 0
	v_cndmask_b32_e32 v181, v3, v153, vcc
	v_cndmask_b32_e32 v180, v2, v155, vcc
	v_cmp_lt_i64_e32 vcc, s[6:7], v[4:5]
	v_lshlrev_b64 v[180:181], 11, v[180:181]
	v_lshl_add_u64 v[188:189], s[0:1], 0, v[180:181]
	v_cndmask_b32_e32 v191, v5, v153, vcc
	v_cndmask_b32_e32 v190, v4, v155, vcc
	v_lshlrev_b64 v[190:191], 11, v[190:191]
	v_lshl_add_u64 v[192:193], s[0:1], 0, v[190:191]
	v_lshl_add_u64 v[180:181], s[66:67], 0, v[180:181]
	v_lshl_add_u64 v[190:191], s[66:67], 0, v[190:191]
	s_setprio 1
	v_lshl_add_u64 v[188:189], v[188:189], 0, s[72:73]
	s_lshl_b32 s6, s88, 14
	v_lshl_add_u64 v[188:189], v[188:189], 0, v[0:1]
	s_add_i32 s7, s87, s6
	s_mov_b32 s8, m0
	s_mov_b32 m0, s7
	s_nop 0
	global_load_lds_dwordx4 v[188:189], off
	s_mov_b32 m0, s8
	v_lshl_add_u64 v[188:189], v[192:193], 0, s[72:73]
	v_mov_b32_e32 v153, v1
	v_lshl_add_u64 v[180:181], v[180:181], 0, s[72:73]
	v_mov_b32_e32 v155, v1
	v_lshl_add_u64 v[188:189], v[188:189], 0, v[152:153]
	s_addk_i32 s7, 0x400
	s_mov_b32 s8, m0
	s_mov_b32 m0, s7
	s_nop 0
	global_load_lds_dwordx4 v[188:189], off
	s_mov_b32 m0, s8
	v_lshl_add_u64 v[180:181], v[180:181], 0, v[154:155]
	s_add_i32 s6, s95, 2
	s_and_b32 s6, s6, 3
	s_lshl_b32 s6, s6, 14
	s_add_i32 s6, s85, s6
	s_mov_b32 s7, m0
	s_mov_b32 m0, s6
	s_nop 0
	global_load_lds_dwordx4 v[180:181], off
	s_mov_b32 m0, s7
	v_lshl_add_u64 v[180:181], v[190:191], 0, s[72:73]
	v_lshl_add_u64 v[180:181], v[180:181], 0, v[154:155]
	s_addk_i32 s6, 0x400
	s_mov_b32 s7, m0
	s_mov_b32 m0, s6
	s_nop 0
	global_load_lds_dwordx4 v[180:181], off
	s_mov_b32 m0, s7
	s_setprio 0
.Lslow_dma_done:
	s_and_b64 vcc, exec, s[4:5]
	s_cbranch_vccz .LBB0_1311
